# v5 + split v_pk_fma_f32/v_pk_add_f32 into scalar f32 ops in the attention phase (packed f32 beside MFMAs)
# baseline (speedup 1.0000x reference)
.LBB0_1053:
	v_mad_i64_i32 v[64:65], s[0:1], v56, s75, 0
	v_mad_i64_i32 v[66:67], s[0:1], v96, s75, 0
	s_movk_i32 s0, 0x70
	s_nop 0
	v_bitop3_b32 v56, v59, v76, s0 bitop3:0x6c
	s_and_b32 s0, s77, 0x3fffffc0
	s_lshl_b32 s0, s0, 2
	s_add_i32 s0, s0, 0
	s_add_i32 s89, s76, 0x100
	s_xor_b64 s[70:71], s[68:69], -1
	s_add_i32 s0, s0, 0x18000
	v_lshlrev_b32_e32 v59, 3, v61
	v_and_b32_e32 v68, 0xc0, v79
	v_lshlrev_b32_e32 v69, 1, v61
	s_lshr_b32 s84, s89, 6
	v_and_or_b32 v68, v59, 24, v68
	v_and_b32_e32 v69, 32, v69
	v_and_b32_e32 v59, 0x100, v59
	s_movk_i32 s1, 0x4000
	s_cmp_lg_u32 0, -1
	v_or3_b32 v59, v68, v69, v59
	v_add3_u32 v68, v78, v56, s1
	s_cselect_b32 s1, 0, 0
	v_add_u32_e32 v197, s1, v59
	v_max_f32_e32 v59, v3, v3
	v_max_f32_e32 v69, v2, v2
	v_max_f32_e32 v59, v69, v59
	v_max3_f32 v56, v18, v19, v20
	v_max3_f32 v59, v59, v4, v8
	v_max3_f32 v56, v56, v24, v25
	v_max3_f32 v59, v59, v9, v10
	v_max3_f32 v56, v56, v26, v27
	v_max3_f32 v59, v59, v11, v12
	v_max3_f32 v56, v56, v28, v29
	v_max3_f32 v59, v59, v13, v14
	v_max3_f32 v56, v56, v30, v31
	v_max3_f32 v59, v59, v15, v16
	v_max3_f32 v70, v5, v6, v7
	v_max3_f32 v56, v56, v32, v33
	v_max3_f32 v69, v21, v22, v23
	v_max3_f32 v59, v59, v17, v70
	v_max3_f32 v56, v56, v69, v59
	v_mov_b32_e32 v59, v56
	s_nop 1
	v_permlane32_swap_b32_e32 v56, v59
	v_max_f32_e32 v59, v59, v59
	v_max_f32_e32 v56, v56, v56
	v_max_f32_e32 v56, v56, v59
	v_add_f32_e32 v59, 0x7149f2ca, v56
	v_mul_f32_e32 v59, 0x3d93cd3a, v59
	v_cmp_ge_f32_e32 vcc, s3, v59
	s_cmp_eq_u64 vcc, exec
	v_max_f32_e32 v56, 0xf149f2ca, v56
	s_cselect_b64 vcc, -1, 0
	v_cndmask_b32_e32 v162, v56, v191, vcc
	v_sub_f32_e32 v59, 0xf149f2ca, v56
	v_mul_f32_e32 v56, 0xbdd53b94, v162
	v_lshl_add_u32 v199, v194, 2, s0
	v_lshl_add_u32 v198, v0, 2, s0
	s_add_i32 s0, s78, 0xffffff80
	v_fma_f32 v160, v2, s74, v56
	v_fma_f32 v161, v3, s74, v56
	v_add_u32_e32 v2, s0, v194
	v_mul_f32_e32 v59, 0x3dd53b94, v59
	v_sub_u32_e32 v218, v2, v0
	v_and_b32_e32 v0, 7, v195
	v_exp_f32_e32 v59, v59
	v_lshl_add_u64 v[2:3], s[42:43], 0, v[66:67]
	v_lshlrev_b32_e32 v0, 4, v0
	v_lshl_add_u64 v[168:169], v[2:3], 0, v[0:1]
	v_and_b32_e32 v0, 15, v195
	v_fma_f32 v32, v32, s74, v56
	v_fma_f32 v33, v33, s74, v56
	v_fma_f32 v30, v30, s74, v56
	v_fma_f32 v31, v31, s74, v56
	v_fma_f32 v28, v28, s74, v56
	v_fma_f32 v29, v29, s74, v56
	v_fma_f32 v26, v26, s74, v56
	v_fma_f32 v27, v27, s74, v56
	v_fma_f32 v24, v24, s74, v56
	v_fma_f32 v25, v25, s74, v56
	v_fma_f32 v22, v22, s74, v56
	v_fma_f32 v23, v23, s74, v56
	v_fma_f32 v20, v20, s74, v56
	v_fma_f32 v21, v21, s74, v56
	v_fma_f32 v18, v18, s74, v56
	v_fma_f32 v19, v19, s74, v56
	s_add_i32 s1, 0, 0x10000
	v_lshl_add_u64 v[2:3], s[42:43], 0, v[64:65]
	v_lshlrev_b32_e32 v0, 4, v0
	v_fma_f32 v148, v14, s74, v56
	v_fma_f32 v149, v15, s74, v56
	v_exp_f32_e32 v144, v18
	v_exp_f32_e32 v145, v19
	v_exp_f32_e32 v142, v20
	v_exp_f32_e32 v143, v21
	v_exp_f32_e32 v140, v22
	v_exp_f32_e32 v141, v23
	v_exp_f32_e32 v138, v24
	v_exp_f32_e32 v139, v25
	v_exp_f32_e32 v136, v26
	v_exp_f32_e32 v137, v27
	v_exp_f32_e32 v134, v28
	v_exp_f32_e32 v135, v29
	v_exp_f32_e32 v132, v30
	v_exp_f32_e32 v133, v31
	v_exp_f32_e32 v130, v32
	v_exp_f32_e32 v131, v33
	v_add_u32_e32 v216, s1, v80
	v_add_u32_e32 v217, s1, v68
	v_lshl_add_u64 v[170:171], v[2:3], 0, v[0:1]
	v_lshl_add_u64 v[2:3], s[40:41], 0, v[54:55]
	v_mov_b32_e32 v14, v1
	v_mov_b32_e32 v15, v1
	v_cndmask_b32_e64 v215, v59, 1.0, vcc
	v_fma_f32 v146, v16, s74, v56
	v_fma_f32 v147, v17, s74, v56
	v_fma_f32 v150, v12, s74, v56
	v_fma_f32 v151, v13, s74, v56
	v_fma_f32 v152, v10, s74, v56
	v_fma_f32 v153, v11, s74, v56
	v_fma_f32 v154, v8, s74, v56
	v_fma_f32 v155, v9, s74, v56
	v_fma_f32 v156, v6, s74, v56
	v_fma_f32 v157, v7, s74, v56
	v_fma_f32 v158, v4, s74, v56
	v_fma_f32 v159, v5, s74, v56
	s_waitcnt vmcnt(0)
	s_waitcnt vmcnt(4)
	ds_write_b128 v202, v[34:37] offset:16384
	s_waitcnt vmcnt(3)
	ds_write_b128 v203, v[38:41] offset:16384
	s_waitcnt vmcnt(2)
	ds_write_b128 v216, v[42:45]
	s_waitcnt vmcnt(1)
	ds_write_b128 v216, v[46:49] offset:8192
	s_waitcnt vmcnt(0)
	ds_write_b128 v217, v[50:53]
	v_add3_u32 v214, s1, v60, v57
	v_add3_u32 v213, s1, v62, v57
	v_add3_u32 v212, s1, v63, v57
	v_add3_u32 v211, s1, v58, v57
	v_cmp_gt_u32_e64 s[4:5], 32, v61
	v_lshl_add_u64 v[172:173], v[2:3], 0, v[0:1]
	v_mov_b32_e32 v0, v1
	v_mov_b32_e32 v2, v1
	v_mov_b32_e32 v3, v1
	v_mov_b32_e32 v4, v1
	v_mov_b32_e32 v5, v1
	v_mov_b32_e32 v6, v1
	v_mov_b32_e32 v7, v1
	v_mov_b32_e32 v8, v1
	v_mov_b32_e32 v9, v1
	v_mov_b32_e32 v10, v1
	v_mov_b32_e32 v11, v1
	v_mov_b32_e32 v12, v1
	v_mov_b32_e32 v13, v1
	v_mov_b64_e32 v[64:65], v[14:15]
	v_mov_b64_e32 v[48:49], v[14:15]
	v_mov_b64_e32 v[32:33], v[14:15]
	v_mov_b64_e32 v[62:63], v[12:13]
	v_mov_b64_e32 v[60:61], v[10:11]
	v_mov_b64_e32 v[58:59], v[8:9]
	v_mov_b64_e32 v[56:57], v[6:7]
	v_mov_b64_e32 v[54:55], v[4:5]
	v_mov_b64_e32 v[52:53], v[2:3]
	v_mov_b64_e32 v[50:51], v[0:1]
	v_mov_b64_e32 v[46:47], v[12:13]
	v_mov_b64_e32 v[44:45], v[10:11]
	v_mov_b64_e32 v[42:43], v[8:9]
	v_mov_b64_e32 v[40:41], v[6:7]
	v_mov_b64_e32 v[38:39], v[4:5]
	v_mov_b64_e32 v[36:37], v[2:3]
	v_mov_b64_e32 v[34:35], v[0:1]
	v_mov_b64_e32 v[30:31], v[12:13]
	v_mov_b64_e32 v[28:29], v[10:11]
	v_mov_b64_e32 v[26:27], v[8:9]
	v_mov_b64_e32 v[24:25], v[6:7]
	v_mov_b64_e32 v[22:23], v[4:5]
	v_mov_b64_e32 v[20:21], v[2:3]
	v_mov_b64_e32 v[18:19], v[0:1]
	v_mov_b64_e32 v[16:17], v[14:15]
	s_mov_b32 s97, s93
	s_mov_b32 s79, 2
	v_mov_b32_e32 v200, 0
	s_movk_i32 s85, 0xbf
	v_mov_b64_e32 v[14:15], v[12:13]
	v_mov_b64_e32 v[12:13], v[10:11]
	v_mov_b64_e32 v[10:11], v[8:9]
	v_mov_b64_e32 v[8:9], v[6:7]
	v_mov_b64_e32 v[6:7], v[4:5]
	v_mov_b64_e32 v[4:5], v[2:3]
	v_mov_b64_e32 v[2:3], v[0:1]
	s_waitcnt lgkmcnt(0)
	s_barrier
.LBB0_1054:
	ds_read_b128 v[66:69], v214
	ds_read_b128 v[70:73], v214 offset:8192
	ds_read_b128 v[174:177], v213
	ds_read_b128 v[178:181], v213 offset:8192
	v_mov_b32_e32 v0, v206
	v_exp_f32_e32 v160, v160
	s_waitcnt lgkmcnt(3)
	v_mfma_f32_32x32x16_bf16 v[82:97], v[66:69], v[98:101], 0
	v_exp_f32_e32 v161, v161
	v_exp_f32_e32 v164, v158
	v_exp_f32_e32 v165, v159
	v_exp_f32_e32 v148, v148
	v_exp_f32_e32 v149, v149
	v_exp_f32_e32 v146, v146
	v_exp_f32_e32 v147, v147
	s_waitcnt lgkmcnt(2)
	v_mfma_f32_32x32x16_bf16 v[66:81], v[70:73], v[98:101], 0
	v_add_f32_e64 v224, v144, v160
	v_add_f32_e64 v225, v145, v161
	s_waitcnt lgkmcnt(1)
	v_mfma_f32_32x32x16_bf16 v[82:97], v[174:177], v[102:105], v[82:97]
	s_waitcnt lgkmcnt(0)
	v_mfma_f32_32x32x16_bf16 v[66:81], v[178:181], v[102:105], v[66:81]
	ds_read_b128 v[174:177], v212
	ds_read_b128 v[178:181], v212 offset:8192
	s_waitcnt lgkmcnt(1)
	v_mfma_f32_32x32x16_bf16 v[82:97], v[174:177], v[106:109], v[82:97]
	s_waitcnt lgkmcnt(0)
	v_mfma_f32_32x32x16_bf16 v[66:81], v[178:181], v[106:109], v[66:81]
	ds_read_b128 v[174:177], v211
	ds_read_b128 v[178:181], v211 offset:8192
	s_nop 0
	v_add_u32_e32 v0, v214, v0
	s_waitcnt lgkmcnt(1)
	v_mfma_f32_32x32x16_bf16 v[82:97], v[174:177], v[110:113], v[82:97]
	s_waitcnt lgkmcnt(0)
	v_mfma_f32_32x32x16_bf16 v[66:81], v[178:181], v[110:113], v[66:81]
	ds_read_b128 v[174:177], v0
	ds_read_b128 v[178:181], v0 offset:8192
	v_mov_b32_e32 v0, v206
	s_nop 0
	v_add_u32_e32 v0, v213, v0
	s_waitcnt lgkmcnt(1)
	v_mfma_f32_32x32x16_bf16 v[82:97], v[174:177], v[114:117], v[82:97]
	s_waitcnt lgkmcnt(0)
	v_mfma_f32_32x32x16_bf16 v[66:81], v[178:181], v[114:117], v[66:81]
	ds_read_b128 v[174:177], v0
	ds_read_b128 v[178:181], v0 offset:8192
	v_mov_b32_e32 v0, v206
	s_nop 0
	v_add_u32_e32 v0, v212, v0
	s_waitcnt lgkmcnt(1)
	v_mfma_f32_32x32x16_bf16 v[82:97], v[174:177], v[118:121], v[82:97]
	s_waitcnt lgkmcnt(0)
	v_mfma_f32_32x32x16_bf16 v[66:81], v[178:181], v[118:121], v[66:81]
	ds_read_b128 v[174:177], v0
	ds_read_b128 v[178:181], v0 offset:8192
	v_mov_b32_e32 v0, v206
	s_nop 0
	v_add_u32_e32 v0, v211, v0
	s_waitcnt lgkmcnt(1)
	v_mfma_f32_32x32x16_bf16 v[82:97], v[174:177], v[122:125], v[82:97]
	s_waitcnt lgkmcnt(0)
	v_mfma_f32_32x32x16_bf16 v[66:81], v[178:181], v[122:125], v[66:81]
	ds_read_b128 v[174:177], v0
	ds_read_b128 v[178:181], v0 offset:8192
	v_add_f32_e32 v0, v224, v225
	s_waitcnt lgkmcnt(1)
	v_mfma_f32_32x32x16_bf16 v[82:97], v[174:177], v[126:129], v[82:97]
	s_waitcnt lgkmcnt(0)
	v_mfma_f32_32x32x16_bf16 v[66:81], v[178:181], v[126:129], v[66:81]
	ds_read_b128 v[174:177], v214 offset:16384
	ds_read_b128 v[178:181], v214 offset:24576
	ds_read_b128 v[220:223], v196
	s_waitcnt lgkmcnt(0)
	v_mfma_f32_32x32x16_bf16 v[82:97], v[174:177], v[220:223], v[82:97]
	v_mfma_f32_32x32x16_bf16 v[66:81], v[178:181], v[220:223], v[66:81]
	ds_read_b128 v[174:177], v213 offset:16384
	ds_read_b128 v[178:181], v213 offset:24576
	ds_read_b128 v[220:223], v196 offset:1024
	s_waitcnt lgkmcnt(0)
	v_mfma_f32_32x32x16_bf16 v[82:97], v[174:177], v[220:223], v[82:97]
	v_mfma_f32_32x32x16_bf16 v[66:81], v[178:181], v[220:223], v[66:81]
	ds_read_b128 v[174:177], v212 offset:16384
	ds_read_b128 v[178:181], v212 offset:24576
	ds_read_b128 v[220:223], v196 offset:2048
	s_waitcnt lgkmcnt(0)
	v_mfma_f32_32x32x16_bf16 v[82:97], v[174:177], v[220:223], v[82:97]
	v_mfma_f32_32x32x16_bf16 v[66:81], v[178:181], v[220:223], v[66:81]
	ds_read_b128 v[174:177], v211 offset:16384
	ds_read_b128 v[178:181], v211 offset:24576
	ds_read_b128 v[220:223], v196 offset:3072
	s_waitcnt lgkmcnt(0)
	v_mfma_f32_32x32x16_bf16 v[82:97], v[174:177], v[220:223], v[82:97]
	v_exp_f32_e32 v174, v156
	v_exp_f32_e32 v175, v157
	v_exp_f32_e32 v176, v154
	v_exp_f32_e32 v177, v155
	s_nop 0
	v_add_f32_e32 v158, v138, v176
	v_add_f32_e32 v159, v139, v177
	v_mfma_f32_32x32x16_bf16 v[66:81], v[178:181], v[220:223], v[66:81]
	v_exp_f32_e32 v178, v152
	v_exp_f32_e32 v179, v153
	v_exp_f32_e32 v180, v150
	v_exp_f32_e32 v181, v151
	v_add_f32_e32 v222, v142, v164
	v_add_f32_e32 v223, v143, v165
	v_add_f32_e32 v150, v130, v146
	v_add_f32_e32 v151, v131, v147
	v_add_f32_e32 v152, v132, v148
	v_add_f32_e32 v153, v133, v149
	v_add_f32_e32 v154, v134, v180
	v_add_f32_e32 v155, v135, v181
	v_add_f32_e32 v156, v136, v178
	v_add_f32_e32 v157, v137, v179
	v_add_f32_e32 v220, v140, v174
	v_add_f32_e32 v221, v141, v175
	v_add_f32_e32 v163, v222, v223
	v_add_f32_e32 v0, v0, v163
	v_add_f32_e32 v163, v220, v221
	v_add_f32_e32 v158, v158, v159
	v_add_f32_e32 v156, v156, v157
	v_add_f32_e32 v154, v154, v155
	v_add_f32_e32 v152, v152, v153
	v_add_f32_e32 v150, v150, v151
	v_add_f32_e32 v158, v163, v158
	v_add_f32_e32 v154, v156, v154
	v_add_f32_e32 v150, v152, v150
	v_add_f32_e32 v0, v0, v158
	v_add_f32_e32 v150, v154, v150
	v_add_f32_e32 v0, v0, v150
	v_mov_b32_e32 v219, v0
	s_nop 1
	v_permlane32_swap_b32_e32 v0, v219
	v_cvt_pk_bf16_f32 v150, v144, v145
	v_cvt_pk_bf16_f32 v151, v142, v143
	v_cvt_pk_bf16_f32 v152, v140, v141
	v_cvt_pk_bf16_f32 v153, v138, v139
	v_cvt_pk_bf16_f32 v154, v136, v137
	v_cvt_pk_bf16_f32 v155, v134, v135
	v_cvt_pk_bf16_f32 v156, v132, v133
	v_cvt_pk_bf16_f32 v157, v130, v131
	v_cvt_pk_bf16_f32 v158, v160, v161
	v_cvt_pk_bf16_f32 v159, v164, v165
	v_cvt_pk_bf16_f32 v160, v174, v175
	v_cvt_pk_bf16_f32 v161, v176, v177
	v_cvt_pk_bf16_f32 v220, v178, v179
	v_cvt_pk_bf16_f32 v221, v180, v181
	v_cvt_pk_bf16_f32 v222, v148, v149
	v_cvt_pk_bf16_f32 v223, v146, v147
	s_nop 0
	v_permlane32_swap_b32_e32 v150, v152
	v_permlane32_swap_b32_e32 v151, v153
	v_permlane32_swap_b32_e32 v154, v156
	v_permlane32_swap_b32_e32 v155, v157
	v_permlane32_swap_b32_e32 v158, v160
	v_permlane32_swap_b32_e32 v159, v161
	v_permlane32_swap_b32_e32 v220, v222
	v_permlane32_swap_b32_e32 v221, v223
	v_lshl_add_u64 v[178:179], s[90:91], 0, v[172:173]
	s_mov_b32 s0, 0x1e880000
	v_add_co_u32_e32 v130, vcc, s0, v178
	s_mov_b32 s0, 0x1e8a0000
	s_nop 0
	v_addc_co_u32_e32 v131, vcc, 0, v179, vcc
	v_add_co_u32_e32 v134, vcc, s0, v178
	v_lshl_add_u64 v[174:175], s[90:91], 0, v[170:171]
	s_nop 0
	v_addc_co_u32_e32 v135, vcc, 0, v179, vcc
	v_add_co_u32_e32 v138, vcc, s86, v174
	s_mov_b32 s0, 0x188f0000
	s_nop 0
	v_addc_co_u32_e32 v139, vcc, 0, v175, vcc
	v_add_co_u32_e32 v142, vcc, s0, v174
	v_lshl_add_u64 v[176:177], s[90:91], 0, v[168:169]
	s_nop 0
	v_addc_co_u32_e32 v143, vcc, 0, v175, vcc
	v_add_co_u32_e32 v146, vcc, s86, v176
	global_load_dwordx4 v[130:133], v[130:131], off
	s_nop 0
	global_load_dwordx4 v[134:137], v[134:135], off
	v_addc_co_u32_e32 v147, vcc, 0, v177, vcc
	global_load_dwordx4 v[138:141], v[138:139], off
	s_nop 0
	global_load_dwordx4 v[142:145], v[142:143], off
	s_nop 0
	global_load_dwordx4 v[146:149], v[146:147], off offset:256
	ds_read_b64_tr_b16 v[224:225], v197 offset:0
	ds_read_b64_tr_b16 v[226:227], v197 offset:0x800
	ds_read_b64_tr_b16 v[228:229], v197 offset:0x1000
	ds_read_b64_tr_b16 v[230:231], v197 offset:0x1800
	ds_read_b64_tr_b16 v[232:233], v197 offset:0x2000
	ds_read_b64_tr_b16 v[234:235], v197 offset:0x2800
	ds_read_b64_tr_b16 v[236:237], v197 offset:0x3000
	ds_read_b64_tr_b16 v[238:239], v197 offset:0x3800
	s_waitcnt lgkmcnt(0)
	s_nop 0
	v_mfma_f32_32x32x16_bf16 v[50:65], v[150:153], v[224:227], v[50:65]
	ds_read_b64_tr_b16 v[224:225], v197 offset:0x200
	ds_read_b64_tr_b16 v[226:227], v197 offset:0xa00
	v_mfma_f32_32x32x16_bf16 v[50:65], v[154:157], v[228:231], v[50:65]
	ds_read_b64_tr_b16 v[228:229], v197 offset:0x1200
	ds_read_b64_tr_b16 v[230:231], v197 offset:0x1a00
	v_mfma_f32_32x32x16_bf16 v[50:65], v[158:161], v[232:235], v[50:65]
	ds_read_b64_tr_b16 v[232:233], v197 offset:0x2200
	ds_read_b64_tr_b16 v[234:235], v197 offset:0x2a00
	ds_read_b64_tr_b16 v[240:241], v197 offset:0x3200
	ds_read_b64_tr_b16 v[242:243], v197 offset:0x3a00
	s_waitcnt lgkmcnt(0)
	v_mfma_f32_32x32x16_bf16 v[50:65], v[220:223], v[236:239], v[50:65]
	v_mfma_f32_32x32x16_bf16 v[34:49], v[150:153], v[224:227], v[34:49]
	ds_read_b64_tr_b16 v[224:225], v197 offset:0x400
	ds_read_b64_tr_b16 v[226:227], v197 offset:0xc00
	v_mfma_f32_32x32x16_bf16 v[34:49], v[154:157], v[228:231], v[34:49]
	ds_read_b64_tr_b16 v[228:229], v197 offset:0x1400
	ds_read_b64_tr_b16 v[230:231], v197 offset:0x1c00
	v_mfma_f32_32x32x16_bf16 v[34:49], v[158:161], v[232:235], v[34:49]
	ds_read_b64_tr_b16 v[232:233], v197 offset:0x2400
	ds_read_b64_tr_b16 v[234:235], v197 offset:0x2c00
	ds_read_b64_tr_b16 v[236:237], v197 offset:0x3400
	ds_read_b64_tr_b16 v[238:239], v197 offset:0x3c00
	s_waitcnt lgkmcnt(0)
	v_mfma_f32_32x32x16_bf16 v[34:49], v[220:223], v[240:243], v[34:49]
	v_mfma_f32_32x32x16_bf16 v[18:33], v[150:153], v[224:227], v[18:33]
	ds_read_b64_tr_b16 v[224:225], v197 offset:0x600
	ds_read_b64_tr_b16 v[226:227], v197 offset:0xe00
	v_mfma_f32_32x32x16_bf16 v[18:33], v[154:157], v[228:231], v[18:33]
	ds_read_b64_tr_b16 v[228:229], v197 offset:0x1600
	ds_read_b64_tr_b16 v[230:231], v197 offset:0x1e00
	v_mfma_f32_32x32x16_bf16 v[18:33], v[158:161], v[232:235], v[18:33]
	ds_read_b64_tr_b16 v[232:233], v197 offset:0x2600
	ds_read_b64_tr_b16 v[234:235], v197 offset:0x2e00
	ds_read_b64_tr_b16 v[240:241], v197 offset:0x3600
	ds_read_b64_tr_b16 v[242:243], v197 offset:0x3e00
	s_waitcnt lgkmcnt(0)
	v_mfma_f32_32x32x16_bf16 v[18:33], v[220:223], v[236:239], v[18:33]
	v_mfma_f32_32x32x16_bf16 v[2:17], v[150:153], v[224:227], v[2:17]
	s_sub_i32 s0, s85, 64
	s_cmp_le_i32 s0, s78
	v_mfma_f32_32x32x16_bf16 v[2:17], v[154:157], v[228:231], v[2:17]
	v_mfma_f32_32x32x16_bf16 v[2:17], v[158:161], v[232:235], v[2:17]
	v_mfma_f32_32x32x16_bf16 v[2:17], v[220:223], v[240:243], v[2:17]
	s_cbranch_scc1 .LBB0_1056
	v_add_u32_e32 v150, 64, v218
	v_cmp_gt_i32_e64 s[66:67], 26, v150
	v_cmp_gt_i32_e64 s[68:69], 27, v150
	v_cmp_gt_i32_e64 s[64:65], 25, v150
	s_and_b64 s[66:67], s[68:69], s[66:67]
	v_cmp_gt_i32_e64 s[62:63], 24, v150
	s_and_b64 s[64:65], s[66:67], s[64:65]
	v_cmp_gt_i32_e64 s[60:61], 19, v150
	s_and_b64 s[62:63], s[64:65], s[62:63]
	v_cmp_gt_i32_e64 s[58:59], 18, v150
	s_and_b64 s[60:61], s[62:63], s[60:61]
	v_cmp_gt_i32_e64 s[56:57], 17, v150
	s_and_b64 s[58:59], s[60:61], s[58:59]
	v_cmp_gt_i32_e64 s[54:55], 16, v150
	s_and_b64 s[56:57], s[58:59], s[56:57]
	v_cmp_gt_i32_e64 s[52:53], 11, v150
	s_and_b64 s[54:55], s[56:57], s[54:55]
	v_cmp_gt_i32_e64 s[50:51], 10, v150
	s_and_b64 s[52:53], s[54:55], s[52:53]
	v_cmp_gt_i32_e64 s[48:49], 9, v150
	s_and_b64 s[50:51], s[52:53], s[50:51]
	v_cmp_gt_i32_e64 s[46:47], 8, v150
	s_and_b64 s[48:49], s[50:51], s[48:49]
	v_cmp_gt_i32_e64 s[44:45], 3, v150
	s_and_b64 s[46:47], s[48:49], s[46:47]
	v_cmp_gt_i32_e64 s[38:39], 2, v150
	s_and_b64 s[44:45], s[46:47], s[44:45]
	v_cmp_gt_i32_e64 s[36:37], 1, v150
	s_and_b64 s[38:39], s[44:45], s[38:39]
	v_cmp_gt_i32_e64 s[0:1], 0, v150
	s_and_b64 s[36:37], s[38:39], s[36:37]
	s_and_b64 s[0:1], s[36:37], s[0:1]
	v_cmp_gt_i32_e64 s[34:35], 58, v150
	v_cndmask_b32_e64 v82, v82, v190, s[0:1]
	v_cmp_gt_i32_e64 s[0:1], 59, v150
	v_cmp_gt_i32_e64 s[30:31], 57, v150
	v_cmp_gt_i32_e64 s[28:29], 56, v150
	v_cndmask_b32_e64 v81, v81, v190, s[0:1]
	s_and_b64 s[0:1], s[0:1], s[34:35]
	v_cndmask_b32_e64 v80, v80, v190, s[0:1]
	s_and_b64 s[0:1], s[0:1], s[30:31]
	v_cmp_gt_i32_e64 s[26:27], 51, v150
	v_cndmask_b32_e64 v79, v79, v190, s[0:1]
	s_and_b64 s[0:1], s[0:1], s[28:29]
	v_cmp_gt_i32_e64 s[24:25], 50, v150
	v_cndmask_b32_e64 v78, v78, v190, s[0:1]
	s_and_b64 s[0:1], s[0:1], s[26:27]
	v_cmp_gt_i32_e64 s[22:23], 49, v150
	v_cndmask_b32_e64 v77, v77, v190, s[0:1]
	s_and_b64 s[0:1], s[0:1], s[24:25]
	v_cmp_gt_i32_e64 s[20:21], 48, v150
	v_cndmask_b32_e64 v76, v76, v190, s[0:1]
	s_and_b64 s[0:1], s[0:1], s[22:23]
	v_cmp_gt_i32_e64 s[18:19], 43, v150
	v_cndmask_b32_e64 v75, v75, v190, s[0:1]
	s_and_b64 s[0:1], s[0:1], s[20:21]
	v_cmp_gt_i32_e64 s[16:17], 42, v150
	v_cndmask_b32_e64 v74, v74, v190, s[0:1]
	s_and_b64 s[0:1], s[0:1], s[18:19]
	v_cmp_gt_i32_e64 s[14:15], 41, v150
	v_cndmask_b32_e64 v73, v73, v190, s[0:1]
	s_and_b64 s[0:1], s[0:1], s[16:17]
	v_cmp_gt_i32_e64 s[12:13], 40, v150
	v_cndmask_b32_e64 v72, v72, v190, s[0:1]
	s_and_b64 s[0:1], s[0:1], s[14:15]
	v_cmp_gt_i32_e64 s[10:11], 35, v150
	v_cndmask_b32_e64 v71, v71, v190, s[0:1]
	s_and_b64 s[0:1], s[0:1], s[12:13]
	v_cmp_gt_i32_e64 s[8:9], 34, v150
	v_cndmask_b32_e64 v70, v70, v190, s[0:1]
	s_and_b64 s[0:1], s[0:1], s[10:11]
	v_cmp_gt_i32_e64 s[6:7], 33, v150
	v_cndmask_b32_e64 v69, v69, v190, s[0:1]
	s_and_b64 s[0:1], s[0:1], s[8:9]
	v_cmp_gt_i32_e32 vcc, 32, v150
	v_cndmask_b32_e64 v68, v68, v190, s[0:1]
	s_and_b64 s[0:1], s[0:1], s[6:7]
	s_and_b64 vcc, s[0:1], vcc
	v_cndmask_b32_e64 v97, v97, v190, s[68:69]
	v_cndmask_b32_e64 v96, v96, v190, s[66:67]
	v_cndmask_b32_e64 v95, v95, v190, s[64:65]
	v_cndmask_b32_e64 v94, v94, v190, s[62:63]
	v_cndmask_b32_e64 v93, v93, v190, s[60:61]
	v_cndmask_b32_e64 v92, v92, v190, s[58:59]
	v_cndmask_b32_e64 v91, v91, v190, s[56:57]
	v_cndmask_b32_e64 v90, v90, v190, s[54:55]
	v_cndmask_b32_e64 v89, v89, v190, s[52:53]
	v_cndmask_b32_e64 v88, v88, v190, s[50:51]
	v_cndmask_b32_e64 v87, v87, v190, s[48:49]
	v_cndmask_b32_e64 v86, v86, v190, s[46:47]
	v_cndmask_b32_e64 v85, v85, v190, s[44:45]
	v_cndmask_b32_e64 v84, v84, v190, s[38:39]
	v_cndmask_b32_e64 v83, v83, v190, s[36:37]
	v_cndmask_b32_e64 v67, v67, v190, s[0:1]
	v_cndmask_b32_e32 v66, v66, v190, vcc

.LBB0_1060:
	v_cndmask_b32_e64 v221, v150, v162, s[6:7]
	v_mul_f32_e32 v180, 0xbdd53b94, v221
	v_mov_b32_e32 v181, v180
	v_fma_f32 v96, v96, s74, v180
	v_fma_f32 v97, v97, s74, v180
	v_fma_f32 v94, v94, s74, v180
	v_fma_f32 v95, v95, s74, v180
	v_fma_f32 v92, v92, s74, v180
	v_fma_f32 v93, v93, s74, v180
	v_fma_f32 v90, v90, s74, v180
	v_fma_f32 v91, v91, s74, v180
	v_fma_f32 v88, v88, s74, v180
	v_fma_f32 v89, v89, s74, v180
	v_fma_f32 v86, v86, s74, v180
	v_fma_f32 v87, v87, s74, v180
	v_fma_f32 v84, v84, s74, v180
	v_fma_f32 v85, v85, s74, v180
	v_fma_f32 v82, v82, s74, v180
	v_fma_f32 v83, v83, s74, v180
	v_exp_f32_e32 v164, v84
	v_exp_f32_e32 v150, v82
	v_exp_f32_e32 v151, v83
	v_exp_f32_e32 v165, v85
	v_exp_f32_e32 v152, v86
	v_exp_f32_e32 v153, v87
	v_exp_f32_e32 v162, v88
	v_exp_f32_e32 v163, v89
	v_exp_f32_e32 v154, v90
	v_exp_f32_e32 v155, v91
	v_exp_f32_e32 v160, v92
	v_exp_f32_e32 v161, v93
	v_exp_f32_e32 v156, v94
	v_exp_f32_e32 v157, v95
	v_exp_f32_e32 v158, v96
	v_exp_f32_e32 v159, v97
	v_mov_b32_e32 v82, v180
	v_mov_b32_e32 v83, v180
	v_fma_f32 v180, v66, s74, v180
	v_fma_f32 v181, v67, s74, v181
	v_fma_f32 v234, v80, s74, v82
	v_fma_f32 v235, v81, s74, v83
	v_fma_f32 v236, v78, s74, v82
	v_fma_f32 v237, v79, s74, v83
	v_fma_f32 v238, v76, s74, v82
	v_fma_f32 v239, v77, s74, v83
	v_fma_f32 v240, v74, s74, v82
	v_fma_f32 v241, v75, s74, v83
	v_fma_f32 v242, v72, s74, v82
	v_fma_f32 v243, v73, s74, v83
	v_fma_f32 v244, v70, s74, v82
	v_fma_f32 v245, v71, s74, v83
	v_fma_f32 v246, v68, s74, v82
	v_fma_f32 v247, v69, s74, v83
	s_waitcnt lgkmcnt(0)
	s_barrier
	ds_read_b128 v[66:69], v207 offset:32768
	ds_read_b128 v[70:73], v207 offset:40960
	ds_read_b128 v[222:225], v208 offset:32768
	ds_read_b128 v[226:229], v208 offset:40960
	v_exp_f32_e32 v236, v236
	v_exp_f32_e32 v237, v237
	s_waitcnt lgkmcnt(3)
	v_mfma_f32_32x32x16_bf16 v[82:97], v[66:69], v[98:101], 0
	v_exp_f32_e32 v234, v234
	v_exp_f32_e32 v235, v235
	s_waitcnt lgkmcnt(2)
	v_mfma_f32_32x32x16_bf16 v[66:81], v[70:73], v[98:101], 0
	s_waitcnt lgkmcnt(1)
	v_mfma_f32_32x32x16_bf16 v[82:97], v[222:225], v[102:105], v[82:97]
	s_waitcnt lgkmcnt(0)
	v_mfma_f32_32x32x16_bf16 v[66:81], v[226:229], v[102:105], v[66:81]
	ds_read_b128 v[222:225], v209 offset:32768
	ds_read_b128 v[226:229], v209 offset:40960
	s_waitcnt lgkmcnt(1)
	v_mfma_f32_32x32x16_bf16 v[82:97], v[222:225], v[106:109], v[82:97]
	s_waitcnt lgkmcnt(0)
	v_mfma_f32_32x32x16_bf16 v[66:81], v[226:229], v[106:109], v[66:81]
	ds_read_b128 v[222:225], v210 offset:32768
	ds_read_b128 v[226:229], v210 offset:40960
	s_waitcnt lgkmcnt(1)
	v_mfma_f32_32x32x16_bf16 v[82:97], v[222:225], v[110:113], v[82:97]
	v_mov_b32_e32 v222, v206
	s_waitcnt lgkmcnt(0)
	v_mfma_f32_32x32x16_bf16 v[66:81], v[226:229], v[110:113], v[66:81]
	v_add_u32_e32 v226, v207, v222
	ds_read_b128 v[222:225], v226 offset:32768
	ds_read_b128 v[226:229], v226 offset:40960
	s_waitcnt lgkmcnt(1)
	v_mfma_f32_32x32x16_bf16 v[82:97], v[222:225], v[114:117], v[82:97]
	v_mov_b32_e32 v222, v206
	s_waitcnt lgkmcnt(0)
	v_mfma_f32_32x32x16_bf16 v[66:81], v[226:229], v[114:117], v[66:81]
	v_add_u32_e32 v226, v208, v222
	ds_read_b128 v[222:225], v226 offset:32768
	ds_read_b128 v[226:229], v226 offset:40960
	s_waitcnt lgkmcnt(1)
	v_mfma_f32_32x32x16_bf16 v[82:97], v[222:225], v[118:121], v[82:97]
	v_mov_b32_e32 v222, v206
	s_waitcnt lgkmcnt(0)
	v_mfma_f32_32x32x16_bf16 v[66:81], v[226:229], v[118:121], v[66:81]
	v_add_u32_e32 v226, v209, v222
	ds_read_b128 v[222:225], v226 offset:32768
	ds_read_b128 v[226:229], v226 offset:40960
	s_waitcnt lgkmcnt(1)
	v_mfma_f32_32x32x16_bf16 v[82:97], v[222:225], v[122:125], v[82:97]
	v_mov_b32_e32 v222, v206
	s_waitcnt lgkmcnt(0)
	v_mfma_f32_32x32x16_bf16 v[66:81], v[226:229], v[122:125], v[66:81]
	v_add_u32_e32 v226, v210, v222
	ds_read_b128 v[222:225], v226 offset:32768
	ds_read_b128 v[226:229], v226 offset:40960
	s_waitcnt lgkmcnt(1)
	v_mfma_f32_32x32x16_bf16 v[82:97], v[222:225], v[126:129], v[82:97]
	s_waitcnt lgkmcnt(0)
	v_mfma_f32_32x32x16_bf16 v[66:81], v[226:229], v[126:129], v[66:81]
	ds_read_b128 v[222:225], v207 offset:49152
	ds_read_b128 v[226:229], v207 offset:57344
	ds_read_b128 v[230:233], v196
	s_waitcnt lgkmcnt(0)
	v_mfma_f32_32x32x16_bf16 v[82:97], v[222:225], v[230:233], v[82:97]
	v_mfma_f32_32x32x16_bf16 v[66:81], v[226:229], v[230:233], v[66:81]
	ds_read_b128 v[222:225], v208 offset:49152
	ds_read_b128 v[226:229], v208 offset:57344
	ds_read_b128 v[230:233], v196 offset:1024
	s_waitcnt lgkmcnt(0)
	v_mfma_f32_32x32x16_bf16 v[82:97], v[222:225], v[230:233], v[82:97]
	v_mfma_f32_32x32x16_bf16 v[66:81], v[226:229], v[230:233], v[66:81]
	ds_read_b128 v[222:225], v209 offset:49152
	ds_read_b128 v[226:229], v209 offset:57344
	ds_read_b128 v[230:233], v196 offset:2048
	s_waitcnt lgkmcnt(0)
	v_mfma_f32_32x32x16_bf16 v[82:97], v[222:225], v[230:233], v[82:97]
	v_mfma_f32_32x32x16_bf16 v[66:81], v[226:229], v[230:233], v[66:81]
	ds_read_b128 v[222:225], v210 offset:49152
	ds_read_b128 v[226:229], v210 offset:57344
	ds_read_b128 v[230:233], v196 offset:3072
	s_waitcnt lgkmcnt(0)
	v_mfma_f32_32x32x16_bf16 v[82:97], v[222:225], v[230:233], v[82:97]
	v_exp_f32_e32 v222, v180
	v_exp_f32_e32 v223, v181
	v_exp_f32_e32 v224, v246
	v_exp_f32_e32 v225, v247
	v_add_f32_e32 v180, v158, v234
	v_add_f32_e32 v181, v159, v235
	v_add_f32_e32 v250, v150, v222
	v_add_f32_e32 v251, v151, v223
	v_add_f32_e32 v180, v180, v181
	v_mfma_f32_32x32x16_bf16 v[66:81], v[226:229], v[230:233], v[66:81]
	v_exp_f32_e32 v226, v244
	v_exp_f32_e32 v227, v245
	v_exp_f32_e32 v228, v242
	v_exp_f32_e32 v229, v243
	v_exp_f32_e32 v230, v240
	v_exp_f32_e32 v231, v241
	v_exp_f32_e32 v232, v238
	v_exp_f32_e32 v233, v239
	v_add_f32_e32 v238, v156, v236
	v_add_f32_e32 v239, v157, v237
	v_add_f32_e32 v242, v154, v230
	v_add_f32_e32 v243, v155, v231
	v_add_f32_e32 v244, v162, v228
	v_add_f32_e32 v245, v163, v229
	v_add_f32_e32 v240, v160, v232
	v_add_f32_e32 v241, v161, v233
	v_add_f32_e32 v246, v152, v226
	v_add_f32_e32 v247, v153, v227
	v_add_f32_e32 v248, v164, v224
	v_add_f32_e32 v249, v165, v225
	v_add_f32_e32 v250, v250, v251
	v_add_f32_e32 v248, v248, v249
	v_add_f32_e32 v246, v246, v247
	v_add_f32_e32 v244, v244, v245
	v_add_f32_e32 v242, v242, v243
	v_add_f32_e32 v240, v240, v241
	v_add_f32_e32 v238, v238, v239
	v_add_f32_e32 v248, v250, v248
	v_add_f32_e32 v244, v246, v244
	v_add_f32_e32 v240, v242, v240
	v_add_f32_e32 v180, v238, v180
	v_add_f32_e32 v244, v248, v244
	v_add_f32_e32 v180, v240, v180
	v_add_f32_e32 v180, v244, v180
	v_mov_b32_e32 v181, v180
	v_cvt_pk_bf16_f32 v150, v150, v151
	v_cvt_pk_bf16_f32 v151, v164, v165
	v_cvt_pk_bf16_f32 v152, v152, v153
	v_cvt_pk_bf16_f32 v153, v162, v163
	v_cvt_pk_bf16_f32 v154, v154, v155
	v_cvt_pk_bf16_f32 v155, v160, v161
	v_cvt_pk_bf16_f32 v156, v156, v157
	v_cvt_pk_bf16_f32 v157, v158, v159
	v_cvt_pk_bf16_f32 v158, v222, v223
	v_cvt_pk_bf16_f32 v159, v224, v225
	v_cvt_pk_bf16_f32 v160, v226, v227
	v_cvt_pk_bf16_f32 v161, v228, v229
	v_cvt_pk_bf16_f32 v162, v230, v231
	v_cvt_pk_bf16_f32 v163, v232, v233
	v_cvt_pk_bf16_f32 v164, v236, v237
	v_cvt_pk_bf16_f32 v165, v234, v235
	s_nop 1
	v_permlane32_swap_b32_e32 v180, v181
	v_permlane32_swap_b32_e32 v150, v152
	v_permlane32_swap_b32_e32 v151, v153
	v_permlane32_swap_b32_e32 v154, v156
	v_permlane32_swap_b32_e32 v155, v157
	v_permlane32_swap_b32_e32 v158, v160
	v_permlane32_swap_b32_e32 v159, v161
	v_permlane32_swap_b32_e32 v162, v164
	v_permlane32_swap_b32_e32 v163, v165
	s_add_i32 s0, s79, 1
	s_cmp_lt_u32 s0, s84
	s_cselect_b64 s[76:77], -1, 0
	s_cmp_ge_u32 s0, s84
	s_cbranch_scc1 .LBB0_1062
	v_add_co_u32_e32 v130, vcc, 0x1e8c0000, v178
	s_nop 1
	v_addc_co_u32_e32 v131, vcc, 0, v179, vcc
	v_add_co_u32_e32 v134, vcc, 0x1e8e0000, v178
	s_nop 1
	v_addc_co_u32_e32 v135, vcc, 0, v179, vcc
	v_add_co_u32_e32 v138, vcc, 0x18920000, v174
	global_load_dwordx4 v[130:133], v[130:131], off
	s_nop 0
	global_load_dwordx4 v[134:137], v[134:135], off
	v_addc_co_u32_e32 v139, vcc, 0, v175, vcc
	v_add_co_u32_e32 v142, vcc, 0x18950000, v174
	s_nop 1
	v_addc_co_u32_e32 v143, vcc, 0, v175, vcc
	v_add_co_u32_e32 v146, vcc, 0x18920000, v176
	global_load_dwordx4 v[138:141], v[138:139], off
	s_nop 0
	global_load_dwordx4 v[142:145], v[142:143], off
	v_addc_co_u32_e32 v147, vcc, 0, v177, vcc
	global_load_dwordx4 v[146:149], v[146:147], off offset:256

.LBB0_1070:
	v_cndmask_b32_e64 v162, v130, v221, s[6:7]
	v_mul_f32_e32 v160, 0xbdd53b94, v162
	v_mov_b32_e32 v161, v160
	v_fma_f32 v96, v96, s74, v160
	v_fma_f32 v97, v97, s74, v160
	v_fma_f32 v94, v94, s74, v160
	v_fma_f32 v95, v95, s74, v160
	v_fma_f32 v92, v92, s74, v160
	v_fma_f32 v93, v93, s74, v160
	v_fma_f32 v90, v90, s74, v160
	v_fma_f32 v91, v91, s74, v160
	v_fma_f32 v88, v88, s74, v160
	v_fma_f32 v89, v89, s74, v160
	v_fma_f32 v86, v86, s74, v160
	v_fma_f32 v87, v87, s74, v160
	v_fma_f32 v84, v84, s74, v160
	v_fma_f32 v85, v85, s74, v160
	v_fma_f32 v82, v82, s74, v160
	v_fma_f32 v83, v83, s74, v160
	s_waitcnt vmcnt(1)
	v_exp_f32_e32 v142, v84
	v_exp_f32_e32 v144, v82
	v_exp_f32_e32 v145, v83
	v_exp_f32_e32 v143, v85
	v_exp_f32_e32 v140, v86
	v_exp_f32_e32 v141, v87
	v_exp_f32_e32 v138, v88
	v_exp_f32_e32 v139, v89
	v_exp_f32_e32 v136, v90
	v_exp_f32_e32 v137, v91
	v_exp_f32_e32 v134, v92
	v_exp_f32_e32 v135, v93
	v_exp_f32_e32 v132, v94
	v_exp_f32_e32 v133, v95
	v_exp_f32_e32 v130, v96
	v_exp_f32_e32 v131, v97
	v_add_f32_e32 v0, v0, v219
	v_mov_b32_e32 v82, v160
	v_mov_b32_e32 v83, v160
	v_fmac_f32_e32 v0, v215, v200
	v_add_f32_e32 v200, v180, v181
	s_addk_i32 s85, 0x80
	s_add_i32 s79, s79, 2
	s_mov_b64 s[0:1], 0x80000
	s_waitcnt vmcnt(0)
	v_fma_f32 v146, v80, s74, v82
	v_fma_f32 v147, v81, s74, v83
	v_fma_f32 v148, v78, s74, v82
	v_fma_f32 v149, v79, s74, v83
	v_fma_f32 v150, v76, s74, v82
	v_fma_f32 v151, v77, s74, v83
	v_fma_f32 v152, v74, s74, v82
	v_fma_f32 v153, v75, s74, v83
	v_fma_f32 v154, v72, s74, v82
	v_fma_f32 v155, v73, s74, v83
	v_fma_f32 v156, v70, s74, v82
	v_fma_f32 v157, v71, s74, v83
	v_fma_f32 v158, v68, s74, v82
	v_fma_f32 v159, v69, s74, v83
	v_fma_f32 v160, v66, s74, v160
	v_fma_f32 v161, v67, s74, v161
	v_fmac_f32_e32 v200, v0, v220
	v_add_u32_e32 v218, 0xffffff80, v218
	v_lshl_add_u64 v[168:169], v[168:169], 0, s[94:95]
	v_lshl_add_u64 v[170:171], v[170:171], 0, s[94:95]
	s_cmp_ge_u32 s79, s84
	v_lshl_add_u64 v[172:173], v[172:173], 0, s[0:1]
	s_waitcnt lgkmcnt(0)
	s_barrier
	s_cbranch_scc1 .LBB0_1072
	v_mov_b32_e32 v215, v163
	s_branch .LBB0_1054
.LBB0_1072:
	ds_read_b128 v[66:69], v214
	ds_read_b128 v[70:73], v214 offset:8192
	v_mov_b32_e32 v0, v206
	s_waitcnt lgkmcnt(1)
	v_mfma_f32_32x32x16_bf16 v[82:97], v[66:69], v[98:101], 0
	s_waitcnt lgkmcnt(0)
	v_mfma_f32_32x32x16_bf16 v[66:81], v[70:73], v[98:101], 0
	ds_read_b128 v[98:101], v213
	ds_read_b128 v[168:171], v213 offset:8192
	s_waitcnt lgkmcnt(1)
	v_mfma_f32_32x32x16_bf16 v[82:97], v[98:101], v[102:105], v[82:97]
	s_waitcnt lgkmcnt(0)
	v_mfma_f32_32x32x16_bf16 v[66:81], v[168:171], v[102:105], v[66:81]
	ds_read_b128 v[98:101], v212
	ds_read_b128 v[102:105], v212 offset:8192
	s_waitcnt lgkmcnt(1)
	v_mfma_f32_32x32x16_bf16 v[82:97], v[98:101], v[106:109], v[82:97]
	s_waitcnt lgkmcnt(0)
	v_mfma_f32_32x32x16_bf16 v[66:81], v[102:105], v[106:109], v[66:81]
	ds_read_b128 v[98:101], v211
	ds_read_b128 v[102:105], v211 offset:8192
	s_nop 0
	v_add_u32_e32 v0, v214, v0
	s_waitcnt lgkmcnt(1)
	v_mfma_f32_32x32x16_bf16 v[82:97], v[98:101], v[110:113], v[82:97]
	s_waitcnt lgkmcnt(0)
	v_mfma_f32_32x32x16_bf16 v[66:81], v[102:105], v[110:113], v[66:81]
	ds_read_b128 v[98:101], v0
	ds_read_b128 v[102:105], v0 offset:8192
	v_mov_b32_e32 v0, v206
	s_nop 0
	v_add_u32_e32 v0, v213, v0
	s_waitcnt lgkmcnt(1)
	v_mfma_f32_32x32x16_bf16 v[82:97], v[98:101], v[114:117], v[82:97]
	s_waitcnt lgkmcnt(0)
	v_mfma_f32_32x32x16_bf16 v[66:81], v[102:105], v[114:117], v[66:81]
	ds_read_b128 v[98:101], v0
	ds_read_b128 v[102:105], v0 offset:8192
	v_mov_b32_e32 v0, v206
	s_nop 0
	v_add_u32_e32 v0, v212, v0
	s_waitcnt lgkmcnt(1)
	v_mfma_f32_32x32x16_bf16 v[82:97], v[98:101], v[118:121], v[82:97]
	s_waitcnt lgkmcnt(0)
	v_mfma_f32_32x32x16_bf16 v[66:81], v[102:105], v[118:121], v[66:81]
	ds_read_b128 v[98:101], v0
	ds_read_b128 v[102:105], v0 offset:8192
	s_nop 0
	v_add_u32_e32 v0, v211, v206
	s_waitcnt lgkmcnt(1)
	v_mfma_f32_32x32x16_bf16 v[82:97], v[98:101], v[122:125], v[82:97]
	s_waitcnt lgkmcnt(0)
	v_mfma_f32_32x32x16_bf16 v[66:81], v[102:105], v[122:125], v[66:81]
	ds_read_b128 v[98:101], v0
	ds_read_b128 v[102:105], v0 offset:8192
	s_waitcnt lgkmcnt(1)
	v_mfma_f32_32x32x16_bf16 v[82:97], v[98:101], v[126:129], v[82:97]
	s_waitcnt lgkmcnt(0)
	v_mfma_f32_32x32x16_bf16 v[66:81], v[102:105], v[126:129], v[66:81]
	ds_read_b128 v[98:101], v214 offset:16384
	ds_read_b128 v[102:105], v196
	ds_read_b128 v[106:109], v214 offset:24576
	ds_read_b128 v[110:113], v196 offset:1024
	s_waitcnt lgkmcnt(2)
	v_mfma_f32_32x32x16_bf16 v[82:97], v[98:101], v[102:105], v[82:97]
	s_waitcnt lgkmcnt(1)
	v_mfma_f32_32x32x16_bf16 v[66:81], v[106:109], v[102:105], v[66:81]
	ds_read_b128 v[98:101], v213 offset:16384
	ds_read_b128 v[102:105], v213 offset:24576
	s_waitcnt lgkmcnt(1)
	v_mfma_f32_32x32x16_bf16 v[82:97], v[98:101], v[110:113], v[82:97]
	s_waitcnt lgkmcnt(0)
	v_mfma_f32_32x32x16_bf16 v[66:81], v[102:105], v[110:113], v[66:81]
	ds_read_b128 v[98:101], v212 offset:16384
	ds_read_b128 v[102:105], v196 offset:2048
	ds_read_b128 v[106:109], v212 offset:24576
	ds_read_b128 v[110:113], v196 offset:3072
	s_waitcnt lgkmcnt(2)
	v_mfma_f32_32x32x16_bf16 v[82:97], v[98:101], v[102:105], v[82:97]
	s_waitcnt lgkmcnt(1)
	v_mfma_f32_32x32x16_bf16 v[66:81], v[106:109], v[102:105], v[66:81]
	ds_read_b128 v[98:101], v211 offset:16384
	ds_read_b128 v[102:105], v211 offset:24576
	s_waitcnt lgkmcnt(1)
	v_mfma_f32_32x32x16_bf16 v[82:97], v[98:101], v[110:113], v[82:97]
	s_waitcnt lgkmcnt(0)
	v_mfma_f32_32x32x16_bf16 v[66:81], v[102:105], v[110:113], v[66:81]
	v_exp_f32_e32 v108, v160
	v_exp_f32_e32 v109, v161
	v_exp_f32_e32 v110, v158
	v_exp_f32_e32 v111, v159
	v_exp_f32_e32 v112, v156
	v_exp_f32_e32 v113, v157
	v_exp_f32_e32 v114, v154
	v_exp_f32_e32 v115, v155
	v_exp_f32_e32 v116, v152
	v_exp_f32_e32 v118, v150
	v_exp_f32_e32 v120, v148
	v_exp_f32_e32 v122, v146
	v_exp_f32_e32 v123, v147
	v_exp_f32_e32 v121, v149
	v_exp_f32_e32 v119, v151
	v_exp_f32_e32 v117, v153
	v_add_f32_e32 v98, v130, v122
	v_add_f32_e32 v99, v131, v123
	v_add_f32_e32 v100, v132, v120
	v_add_f32_e32 v101, v133, v121
	v_add_f32_e32 v102, v134, v118
	v_add_f32_e32 v103, v135, v119
	v_add_f32_e32 v104, v136, v116
	v_add_f32_e32 v105, v137, v117
	v_add_f32_e32 v106, v138, v114
	v_add_f32_e32 v107, v139, v115
	v_add_f32_e32 v124, v140, v112
	v_add_f32_e32 v125, v141, v113
	v_add_f32_e32 v126, v142, v110
	v_add_f32_e32 v127, v143, v111
	v_add_f32_e32 v128, v144, v108
	v_add_f32_e32 v129, v145, v109
	v_add_f32_e32 v126, v126, v127
	v_add_f32_e32 v0, v128, v129
	v_add_f32_e32 v124, v124, v125
	v_add_f32_e32 v106, v106, v107
	v_add_f32_e32 v104, v104, v105
	v_add_f32_e32 v102, v102, v103
	v_add_f32_e32 v100, v100, v101
	v_add_f32_e32 v98, v98, v99
	v_add_f32_e32 v0, v0, v126
	v_add_f32_e32 v106, v124, v106
	v_add_f32_e32 v102, v104, v102
	v_add_f32_e32 v98, v100, v98
	v_add_f32_e32 v0, v0, v106
	v_add_f32_e32 v98, v102, v98
	v_add_f32_e32 v0, v0, v98
	v_mov_b32_e32 v98, v0
	s_nop 1
	v_permlane32_swap_b32_e32 v0, v98
	v_cvt_pk_bf16_f32 v100, v144, v145
	v_cvt_pk_bf16_f32 v101, v142, v143
	v_cvt_pk_bf16_f32 v102, v140, v141
	v_cvt_pk_bf16_f32 v103, v138, v139
	v_cvt_pk_bf16_f32 v104, v136, v137
	v_cvt_pk_bf16_f32 v105, v134, v135
	v_cvt_pk_bf16_f32 v106, v132, v133
	v_cvt_pk_bf16_f32 v107, v130, v131
	v_cvt_pk_bf16_f32 v108, v108, v109
	v_cvt_pk_bf16_f32 v109, v110, v111
	v_cvt_pk_bf16_f32 v110, v112, v113
	v_cvt_pk_bf16_f32 v111, v114, v115
	v_cvt_pk_bf16_f32 v112, v116, v117
	v_cvt_pk_bf16_f32 v113, v118, v119
	v_cvt_pk_bf16_f32 v114, v120, v121
	v_cvt_pk_bf16_f32 v115, v122, v123
	s_nop 0
	v_permlane32_swap_b32_e32 v100, v102
	v_permlane32_swap_b32_e32 v101, v103
	v_permlane32_swap_b32_e32 v104, v106
	v_permlane32_swap_b32_e32 v105, v107
	v_permlane32_swap_b32_e32 v108, v110
	v_permlane32_swap_b32_e32 v109, v111
	v_permlane32_swap_b32_e32 v112, v114
	v_permlane32_swap_b32_e32 v113, v115
	ds_read_b64_tr_b16 v[116:117], v197 offset:0
	ds_read_b64_tr_b16 v[118:119], v197 offset:0x800
	ds_read_b64_tr_b16 v[120:121], v197 offset:0x1000
	ds_read_b64_tr_b16 v[122:123], v197 offset:0x1800
	ds_read_b64_tr_b16 v[124:125], v197 offset:0x2000
	ds_read_b64_tr_b16 v[126:127], v197 offset:0x2800
	ds_read_b64_tr_b16 v[128:129], v197 offset:0x3000
	ds_read_b64_tr_b16 v[130:131], v197 offset:0x3800
	s_waitcnt lgkmcnt(0)
	s_nop 0
	v_mfma_f32_32x32x16_bf16 v[50:65], v[100:103], v[116:119], v[50:65]
	ds_read_b64_tr_b16 v[116:117], v197 offset:0x200
	ds_read_b64_tr_b16 v[118:119], v197 offset:0xa00
	v_mfma_f32_32x32x16_bf16 v[50:65], v[104:107], v[120:123], v[50:65]
	ds_read_b64_tr_b16 v[120:121], v197 offset:0x1200
	ds_read_b64_tr_b16 v[122:123], v197 offset:0x1a00
	v_mfma_f32_32x32x16_bf16 v[50:65], v[108:111], v[124:127], v[50:65]
	ds_read_b64_tr_b16 v[124:125], v197 offset:0x2200
	ds_read_b64_tr_b16 v[126:127], v197 offset:0x2a00
	ds_read_b64_tr_b16 v[132:133], v197 offset:0x3200
	ds_read_b64_tr_b16 v[134:135], v197 offset:0x3a00
	s_waitcnt lgkmcnt(0)
	v_mfma_f32_32x32x16_bf16 v[50:65], v[112:115], v[128:131], v[50:65]
	v_mfma_f32_32x32x16_bf16 v[34:49], v[100:103], v[116:119], v[34:49]
	ds_read_b64_tr_b16 v[116:117], v197 offset:0x400
	ds_read_b64_tr_b16 v[118:119], v197 offset:0xc00
	v_mfma_f32_32x32x16_bf16 v[34:49], v[104:107], v[120:123], v[34:49]
	ds_read_b64_tr_b16 v[120:121], v197 offset:0x1400
	ds_read_b64_tr_b16 v[122:123], v197 offset:0x1c00
	v_mfma_f32_32x32x16_bf16 v[34:49], v[108:111], v[124:127], v[34:49]
	ds_read_b64_tr_b16 v[124:125], v197 offset:0x2400
	ds_read_b64_tr_b16 v[126:127], v197 offset:0x2c00
	ds_read_b64_tr_b16 v[128:129], v197 offset:0x3400
	ds_read_b64_tr_b16 v[130:131], v197 offset:0x3c00
	s_waitcnt lgkmcnt(0)
	v_mfma_f32_32x32x16_bf16 v[34:49], v[112:115], v[132:135], v[34:49]
	v_mfma_f32_32x32x16_bf16 v[18:33], v[100:103], v[116:119], v[18:33]
	ds_read_b64_tr_b16 v[116:117], v197 offset:0x600
	ds_read_b64_tr_b16 v[118:119], v197 offset:0xe00
	v_mfma_f32_32x32x16_bf16 v[18:33], v[104:107], v[120:123], v[18:33]
	ds_read_b64_tr_b16 v[120:121], v197 offset:0x1600
	ds_read_b64_tr_b16 v[122:123], v197 offset:0x1e00
	v_mfma_f32_32x32x16_bf16 v[18:33], v[108:111], v[124:127], v[18:33]
	ds_read_b64_tr_b16 v[124:125], v197 offset:0x2600
	ds_read_b64_tr_b16 v[126:127], v197 offset:0x2e00
	ds_read_b64_tr_b16 v[132:133], v197 offset:0x3600
	ds_read_b64_tr_b16 v[134:135], v197 offset:0x3e00
	s_waitcnt lgkmcnt(0)
	v_mfma_f32_32x32x16_bf16 v[18:33], v[112:115], v[128:131], v[18:33]
	v_mfma_f32_32x32x16_bf16 v[2:17], v[100:103], v[116:119], v[2:17]
	s_cmp_lt_i32 s73, 8
	v_mfma_f32_32x32x16_bf16 v[2:17], v[104:107], v[120:123], v[2:17]
	v_mfma_f32_32x32x16_bf16 v[2:17], v[108:111], v[124:127], v[2:17]
	v_mfma_f32_32x32x16_bf16 v[2:17], v[112:115], v[132:135], v[2:17]
	s_cbranch_scc0 .LBB0_1074
	v_subrev_u32_e32 v99, s89, v201
	s_movk_i32 s36, 0xffda
	s_movk_i32 s68, 0xffdb
	s_movk_i32 s30, 0xffd9
	v_cmp_gt_i32_e64 s[66:67], s36, v99
	v_cmp_gt_i32_e64 s[68:69], s68, v99
	s_movk_i32 s28, 0xffd8
	v_cmp_gt_i32_e64 s[64:65], s30, v99
	s_and_b64 s[66:67], s[68:69], s[66:67]
	s_movk_i32 s26, 0xffd3
	v_cmp_gt_i32_e64 s[62:63], s28, v99
	s_and_b64 s[64:65], s[66:67], s[64:65]
	s_movk_i32 s24, 0xffd2
	v_cmp_gt_i32_e64 s[60:61], s26, v99
	s_and_b64 s[62:63], s[64:65], s[62:63]
	s_movk_i32 s22, 0xffd1
	v_cmp_gt_i32_e64 s[58:59], s24, v99
	s_and_b64 s[60:61], s[62:63], s[60:61]
	s_movk_i32 s20, 0xffd0
	v_cmp_gt_i32_e64 s[56:57], s22, v99
	s_and_b64 s[58:59], s[60:61], s[58:59]
	s_movk_i32 s18, 0xffcb
	v_cmp_gt_i32_e64 s[54:55], s20, v99
	s_and_b64 s[56:57], s[58:59], s[56:57]
	s_movk_i32 s0, 0xffc0
	s_movk_i32 s16, 0xffca
	v_cmp_gt_i32_e64 s[52:53], s18, v99
	s_and_b64 s[54:55], s[56:57], s[54:55]
	v_cmp_gt_i32_e64 s[34:35], s0, v99
	s_movk_i32 s0, 0xffe0
	s_movk_i32 s14, 0xffc9
	v_cmp_gt_i32_e64 s[50:51], s16, v99
	s_and_b64 s[52:53], s[54:55], s[52:53]
	v_cmp_gt_i32_e32 vcc, s0, v99
	s_movk_i32 s0, 0xffc1
	s_movk_i32 s12, 0xffc8
	v_cmp_gt_i32_e64 s[48:49], s14, v99
	s_and_b64 s[50:51], s[52:53], s[50:51]
	v_cmp_gt_i32_e64 s[38:39], s0, v99
	s_movk_i32 s0, 0xffe1
	s_movk_i32 s10, 0xffc3
	v_cmp_gt_i32_e64 s[46:47], s12, v99
	s_and_b64 s[48:49], s[50:51], s[48:49]
	v_cmp_gt_i32_e64 s[6:7], s0, v99
	s_movk_i32 s0, 0xffc2
	v_cmp_gt_i32_e64 s[44:45], s10, v99
	s_and_b64 s[46:47], s[48:49], s[46:47]
	v_cmp_gt_i32_e64 s[0:1], s0, v99
	s_and_b64 s[44:45], s[46:47], s[44:45]
	s_and_b64 s[0:1], s[44:45], s[0:1]
	v_cndmask_b32_e64 v84, v84, v190, s[0:1]
	s_and_b64 s[0:1], s[0:1], s[38:39]
	v_cndmask_b32_e64 v83, v83, v190, s[0:1]
	s_and_b64 s[0:1], s[0:1], s[34:35]
	v_cmp_gt_i32_e64 s[36:37], -6, v99
	v_cndmask_b32_e64 v82, v82, v190, s[0:1]
	v_cmp_gt_i32_e64 s[0:1], -5, v99
	v_cmp_gt_i32_e64 s[30:31], -7, v99
	v_cmp_gt_i32_e64 s[28:29], -8, v99
	v_cndmask_b32_e64 v81, v81, v190, s[0:1]
	s_and_b64 s[0:1], s[0:1], s[36:37]
	v_cndmask_b32_e64 v80, v80, v190, s[0:1]
	s_and_b64 s[0:1], s[0:1], s[30:31]
	v_cmp_gt_i32_e64 s[26:27], -13, v99
	v_cndmask_b32_e64 v79, v79, v190, s[0:1]
	s_and_b64 s[0:1], s[0:1], s[28:29]
	v_cmp_gt_i32_e64 s[24:25], -14, v99
	v_cndmask_b32_e64 v78, v78, v190, s[0:1]
	s_and_b64 s[0:1], s[0:1], s[26:27]
	v_cmp_gt_i32_e64 s[22:23], -15, v99
	v_cndmask_b32_e64 v77, v77, v190, s[0:1]
	s_and_b64 s[0:1], s[0:1], s[24:25]
	s_movk_i32 s18, 0xffeb
	v_cmp_gt_i32_e64 s[20:21], -16, v99
	v_cndmask_b32_e64 v76, v76, v190, s[0:1]
	s_and_b64 s[0:1], s[0:1], s[22:23]
	s_movk_i32 s16, 0xffea
	v_cmp_gt_i32_e64 s[18:19], s18, v99
	v_cndmask_b32_e64 v75, v75, v190, s[0:1]
	s_and_b64 s[0:1], s[0:1], s[20:21]
	s_movk_i32 s14, 0xffe9
	v_cmp_gt_i32_e64 s[16:17], s16, v99
	v_cndmask_b32_e64 v74, v74, v190, s[0:1]
	s_and_b64 s[0:1], s[0:1], s[18:19]
	s_movk_i32 s12, 0xffe8
	v_cmp_gt_i32_e64 s[14:15], s14, v99
	v_cndmask_b32_e64 v73, v73, v190, s[0:1]
	s_and_b64 s[0:1], s[0:1], s[16:17]
	s_movk_i32 s10, 0xffe3
	v_cmp_gt_i32_e64 s[12:13], s12, v99
	v_cndmask_b32_e64 v72, v72, v190, s[0:1]
	s_and_b64 s[0:1], s[0:1], s[14:15]
	s_movk_i32 s8, 0xffe2
	v_cmp_gt_i32_e64 s[10:11], s10, v99
	v_cndmask_b32_e64 v71, v71, v190, s[0:1]
	s_and_b64 s[0:1], s[0:1], s[12:13]
	v_cmp_gt_i32_e64 s[8:9], s8, v99
	v_cndmask_b32_e64 v70, v70, v190, s[0:1]
	s_and_b64 s[0:1], s[0:1], s[10:11]
	v_cndmask_b32_e64 v69, v69, v190, s[0:1]
	s_and_b64 s[0:1], s[0:1], s[8:9]
	v_cndmask_b32_e64 v68, v68, v190, s[0:1]
	s_and_b64 s[0:1], s[0:1], s[6:7]
	s_and_b64 vcc, s[0:1], vcc
	v_cndmask_b32_e64 v97, v97, v190, s[68:69]
	v_cndmask_b32_e64 v96, v96, v190, s[66:67]
	v_cndmask_b32_e64 v95, v95, v190, s[64:65]
	v_cndmask_b32_e64 v94, v94, v190, s[62:63]
	v_cndmask_b32_e64 v93, v93, v190, s[60:61]
	v_cndmask_b32_e64 v92, v92, v190, s[58:59]
	v_cndmask_b32_e64 v91, v91, v190, s[56:57]
	v_cndmask_b32_e64 v90, v90, v190, s[54:55]
	v_cndmask_b32_e64 v89, v89, v190, s[52:53]
	v_cndmask_b32_e64 v88, v88, v190, s[50:51]
	v_cndmask_b32_e64 v87, v87, v190, s[48:49]
	v_cndmask_b32_e64 v86, v86, v190, s[46:47]
	v_cndmask_b32_e64 v85, v85, v190, s[44:45]
	v_cndmask_b32_e64 v67, v67, v190, s[0:1]
	v_cndmask_b32_e32 v66, v66, v190, vcc

.LBB0_1078:
	v_cndmask_b32_e64 v100, v100, v162, s[6:7]
	v_mul_f32_e32 v100, 0xbdd53b94, v100
	v_fma_f32 v96, v96, s74, v100
	v_fma_f32 v97, v97, s74, v100
	v_fma_f32 v94, v94, s74, v100
	v_fma_f32 v95, v95, s74, v100
	v_fma_f32 v92, v92, s74, v100
	v_fma_f32 v93, v93, s74, v100
	v_fma_f32 v90, v90, s74, v100
	v_fma_f32 v91, v91, s74, v100
	v_fma_f32 v88, v88, s74, v100
	v_fma_f32 v89, v89, s74, v100
	v_fma_f32 v86, v86, s74, v100
	v_fma_f32 v87, v87, s74, v100
	v_fma_f32 v84, v84, s74, v100
	v_fma_f32 v85, v85, s74, v100
	v_fma_f32 v82, v82, s74, v100
	v_fma_f32 v83, v83, s74, v100
	v_fma_f32 v80, v80, s74, v100
	v_fma_f32 v81, v81, s74, v100
	v_fma_f32 v78, v78, s74, v100
	v_fma_f32 v79, v79, s74, v100
	v_fma_f32 v76, v76, s74, v100
	v_fma_f32 v77, v77, s74, v100
	v_fma_f32 v74, v74, s74, v100
	v_fma_f32 v75, v75, s74, v100
	v_fma_f32 v72, v72, s74, v100
	v_fma_f32 v73, v73, s74, v100
	v_fma_f32 v70, v70, s74, v100
	v_fma_f32 v71, v71, s74, v100
	v_fma_f32 v68, v68, s74, v100
	v_fma_f32 v69, v69, s74, v100
	v_fma_f32 v66, v66, s74, v100
	v_fma_f32 v67, v67, s74, v100
	v_exp_f32_e32 v82, v82
	v_exp_f32_e32 v83, v83
	v_exp_f32_e32 v84, v84
	v_exp_f32_e32 v85, v85
	v_exp_f32_e32 v86, v86
	v_exp_f32_e32 v87, v87
	v_exp_f32_e32 v88, v88
	v_exp_f32_e32 v89, v89
	v_exp_f32_e32 v90, v90
	v_exp_f32_e32 v91, v91
	v_exp_f32_e32 v92, v92
	v_exp_f32_e32 v93, v93
	v_exp_f32_e32 v94, v94
	v_exp_f32_e32 v95, v95
	v_exp_f32_e32 v96, v96
	v_exp_f32_e32 v97, v97
	v_exp_f32_e32 v100, v66
	v_exp_f32_e32 v101, v67
	v_exp_f32_e32 v102, v68
	v_exp_f32_e32 v103, v69
	v_exp_f32_e32 v104, v70
	v_exp_f32_e32 v105, v71
	v_exp_f32_e32 v106, v72
	v_exp_f32_e32 v107, v73
	v_exp_f32_e32 v108, v74
	v_exp_f32_e32 v110, v76
	v_exp_f32_e32 v112, v78
	v_exp_f32_e32 v114, v80
	v_exp_f32_e32 v115, v81
	v_exp_f32_e32 v113, v79
	v_exp_f32_e32 v111, v77
	v_exp_f32_e32 v109, v75
	v_add_f32_e32 v66, v96, v114
	v_add_f32_e32 v67, v97, v115
	v_add_f32_e32 v68, v94, v112
	v_add_f32_e32 v69, v95, v113
	v_add_f32_e32 v70, v92, v110
	v_add_f32_e32 v71, v93, v111
	v_add_f32_e32 v72, v90, v108
	v_add_f32_e32 v73, v91, v109
	v_add_f32_e32 v74, v88, v106
	v_add_f32_e32 v75, v89, v107
	v_add_f32_e32 v76, v86, v104
	v_add_f32_e32 v77, v87, v105
	v_add_f32_e32 v78, v84, v102
	v_add_f32_e32 v79, v85, v103
	v_add_f32_e32 v80, v82, v100
	v_add_f32_e32 v81, v83, v101
	v_add_f32_e32 v78, v78, v79
	v_add_f32_e32 v80, v80, v81
	v_add_f32_e32 v76, v76, v77
	v_add_f32_e32 v74, v74, v75
	v_add_f32_e32 v72, v72, v73
	v_add_f32_e32 v70, v70, v71
	v_add_f32_e32 v68, v68, v69
	v_add_f32_e32 v66, v66, v67
	v_add_f32_e32 v78, v80, v78
	v_add_f32_e32 v74, v76, v74
	v_add_f32_e32 v70, v72, v70
	v_add_f32_e32 v66, v68, v66
	v_add_f32_e32 v74, v78, v74
	v_add_f32_e32 v66, v70, v66
	v_add_f32_e32 v66, v74, v66
	v_mov_b32_e32 v67, v66
	s_nop 1
	v_permlane32_swap_b32_e32 v66, v67
	v_cvt_pk_bf16_f32 v68, v82, v83
	v_cvt_pk_bf16_f32 v69, v84, v85
	v_cvt_pk_bf16_f32 v70, v86, v87
	v_cvt_pk_bf16_f32 v71, v88, v89
	v_cvt_pk_bf16_f32 v72, v90, v91
	v_cvt_pk_bf16_f32 v73, v92, v93
	v_cvt_pk_bf16_f32 v74, v94, v95
	v_cvt_pk_bf16_f32 v75, v96, v97
	v_cvt_pk_bf16_f32 v76, v100, v101
	v_cvt_pk_bf16_f32 v77, v102, v103
	v_cvt_pk_bf16_f32 v78, v104, v105
	v_cvt_pk_bf16_f32 v79, v106, v107
	v_cvt_pk_bf16_f32 v80, v108, v109
	v_cvt_pk_bf16_f32 v81, v110, v111
	v_cvt_pk_bf16_f32 v82, v112, v113
	v_cvt_pk_bf16_f32 v83, v114, v115
	s_nop 0
	v_permlane32_swap_b32_e32 v68, v70
	v_permlane32_swap_b32_e32 v69, v71
	v_permlane32_swap_b32_e32 v72, v74
	v_permlane32_swap_b32_e32 v73, v75
	v_permlane32_swap_b32_e32 v76, v78
	v_permlane32_swap_b32_e32 v77, v79
	v_permlane32_swap_b32_e32 v80, v82
	v_permlane32_swap_b32_e32 v81, v83
	ds_read_b64_tr_b16 v[84:85], v197 offset:0x4000
	ds_read_b64_tr_b16 v[86:87], v197 offset:0x4800
	ds_read_b64_tr_b16 v[88:89], v197 offset:0x5000
	ds_read_b64_tr_b16 v[90:91], v197 offset:0x5800
	ds_read_b64_tr_b16 v[92:93], v197 offset:0x6000
	ds_read_b64_tr_b16 v[94:95], v197 offset:0x6800
	ds_read_b64_tr_b16 v[100:101], v197 offset:0x7000
	ds_read_b64_tr_b16 v[102:103], v197 offset:0x7800
	s_waitcnt lgkmcnt(0)
	s_nop 0
	v_mfma_f32_32x32x16_bf16 v[50:65], v[68:71], v[84:87], v[50:65]
	ds_read_b64_tr_b16 v[84:85], v197 offset:0x4200
	ds_read_b64_tr_b16 v[86:87], v197 offset:0x4a00
	v_mfma_f32_32x32x16_bf16 v[50:65], v[72:75], v[88:91], v[50:65]
	ds_read_b64_tr_b16 v[88:89], v197 offset:0x5200
	ds_read_b64_tr_b16 v[90:91], v197 offset:0x5a00
	v_mfma_f32_32x32x16_bf16 v[50:65], v[76:79], v[92:95], v[50:65]
	ds_read_b64_tr_b16 v[92:93], v197 offset:0x6200
	ds_read_b64_tr_b16 v[94:95], v197 offset:0x6a00
	ds_read_b64_tr_b16 v[104:105], v197 offset:0x7200
	ds_read_b64_tr_b16 v[106:107], v197 offset:0x7a00
	s_waitcnt lgkmcnt(0)
	v_mfma_f32_32x32x16_bf16 v[50:65], v[80:83], v[100:103], v[50:65]
	v_mfma_f32_32x32x16_bf16 v[34:49], v[68:71], v[84:87], v[34:49]
	ds_read_b64_tr_b16 v[84:85], v197 offset:0x4400
	ds_read_b64_tr_b16 v[86:87], v197 offset:0x4c00
	v_mfma_f32_32x32x16_bf16 v[34:49], v[72:75], v[88:91], v[34:49]
	ds_read_b64_tr_b16 v[88:89], v197 offset:0x5400
	ds_read_b64_tr_b16 v[90:91], v197 offset:0x5c00
	v_mfma_f32_32x32x16_bf16 v[34:49], v[76:79], v[92:95], v[34:49]
	ds_read_b64_tr_b16 v[92:93], v197 offset:0x6400
	ds_read_b64_tr_b16 v[94:95], v197 offset:0x6c00
	ds_read_b64_tr_b16 v[100:101], v197 offset:0x7400
	ds_read_b64_tr_b16 v[102:103], v197 offset:0x7c00
	s_waitcnt lgkmcnt(0)
	v_mfma_f32_32x32x16_bf16 v[34:49], v[80:83], v[104:107], v[34:49]
	v_mfma_f32_32x32x16_bf16 v[18:33], v[68:71], v[84:87], v[18:33]
	ds_read_b64_tr_b16 v[84:85], v197 offset:0x4600
	ds_read_b64_tr_b16 v[86:87], v197 offset:0x4e00
	v_mfma_f32_32x32x16_bf16 v[18:33], v[72:75], v[88:91], v[18:33]
	ds_read_b64_tr_b16 v[88:89], v197 offset:0x5600
	ds_read_b64_tr_b16 v[90:91], v197 offset:0x5e00
	v_mfma_f32_32x32x16_bf16 v[18:33], v[76:79], v[92:95], v[18:33]
	ds_read_b64_tr_b16 v[92:93], v197 offset:0x6600
	ds_read_b64_tr_b16 v[94:95], v197 offset:0x6e00
	ds_read_b64_tr_b16 v[104:105], v197 offset:0x7600
	ds_read_b64_tr_b16 v[106:107], v197 offset:0x7e00
	s_waitcnt lgkmcnt(0)
	v_mfma_f32_32x32x16_bf16 v[18:33], v[80:83], v[100:103], v[18:33]
	v_mfma_f32_32x32x16_bf16 v[2:17], v[68:71], v[84:87], v[2:17]
	v_mfma_f32_32x32x16_bf16 v[2:17], v[72:75], v[88:91], v[2:17]
	v_mfma_f32_32x32x16_bf16 v[2:17], v[76:79], v[92:95], v[2:17]
	v_mfma_f32_32x32x16_bf16 v[2:17], v[80:83], v[104:107], v[2:17]
	s_and_saveexec_b64 s[0:1], s[4:5]
	v_add_f32_e32 v0, v0, v98
	v_fmac_f32_e32 v0, v200, v163
	v_add_f32_e32 v66, v66, v67
	v_fmac_f32_e32 v66, v0, v99
	ds_write_b32 v199, v66
	s_or_b64 exec, exec, s[0:1]
	s_waitcnt lgkmcnt(0)
	ds_read_b128 v[78:81], v198
	ds_read_b128 v[74:77], v198 offset:32
	v_xor_b32_e32 v0, 1, v192
	s_lshl_b64 s[0:1], s[96:97], 12
	v_readlane_b32 s4, v254, 51
	s_waitcnt lgkmcnt(1)
	v_rcp_f32_e32 v84, v78
	v_and_b32_e32 v78, 64, v192
	v_add_u32_e32 v78, 64, v78
	v_cmp_lt_i32_e32 vcc, v0, v78
	s_add_u32 s4, s4, s0
	s_addc_u32 s5, s33, s1
	v_cndmask_b32_e32 v0, v192, v0, vcc
	s_ashr_i32 s89, s88, 31
	v_lshlrev_b32_e32 v78, 2, v0
	v_mul_f32_e32 v50, v50, v84
	ds_read_b128 v[70:73], v198 offset:64
	ds_read_b128 v[66:69], v198 offset:96
	s_lshl_b64 s[0:1], s[88:89], 12
	ds_bpermute_b32 v85, v78, v50
	s_add_u32 s0, s4, s0
	v_and_b32_e32 v0, 1, v195
	s_addc_u32 s1, s5, s1
	v_cmp_eq_u32_e64 s[4:5], 0, v0
	v_lshlrev_b32_e32 v0, 1, v194
	v_lshl_add_u64 v[82:83], s[0:1], 0, v[0:1]
	v_lshlrev_b32_e32 v0, 14, v193
	v_lshl_add_u64 v[82:83], v[82:83], 0, v[0:1]
	s_and_saveexec_b64 s[0:1], s[4:5]
	s_cbranch_execz .LBB0_1082
	s_waitcnt lgkmcnt(0)
	v_cvt_pk_bf16_f32 v0, v50, v85
	global_store_dword v[82:83], v0, off
